# all GEMM K-loops: LDS-DMA loads with unshared addresses in scalar-base + 32-bit offset form (64-bit VALU address adds removed from the load sections)
# speedup vs baseline: 1.0022x; 1.0022x over previous
.LBB0_288:
	s_add_u32 s30, s28, 0xfffc0080
	s_addc_u32 s31, s29, -1
	s_add_i32 s56, 0, 0x10000
	s_cmp_eq_u32 s55, 12
	s_cselect_b32 s35, s21, s31
	s_cselect_b32 s34, s36, s30
	s_cselect_b32 s31, s19, s39
	s_cselect_b32 s30, s37, s38
	s_add_i32 s58, 0, 0x14000
	v_add_u32_e32 v166, s56, v147
	v_add_u32_e32 v182, s58, v147
	ds_read_b128 v[142:145], v166
	ds_read_b128 v[158:161], v166 offset:1024
	ds_read_b128 v[162:165], v166 offset:2048
	ds_read_b128 v[166:169], v166 offset:3072
	ds_read_b128 v[170:173], v182
	ds_read_b128 v[174:177], v182 offset:1024
	ds_read_b128 v[178:181], v182 offset:2048
	ds_read_b128 v[182:185], v182 offset:3072
	s_add_i32 m0, s44, 0xc000
	ds_read_b128 v[186:189], v157
	ds_read_b128 v[190:193], v157 offset:1024
	ds_read_b128 v[194:197], v157 offset:2048
	ds_read_b128 v[198:201], v157 offset:3072
	ds_read_b128 v[202:205], v157 offset:4096
	ds_read_b128 v[206:209], v157 offset:5120
	ds_read_b128 v[220:223], v157 offset:6144
	ds_read_b128 v[236:239], v157 offset:7168
	global_load_lds_dwordx4 v140, s[28:29]
	s_add_i32 m0, s44, 0xe000
	s_nop 0
	global_load_lds_dwordx4 v138, s[28:29]
	s_branch .Lpadj_4
	s_nop 0
	s_nop 0
	s_nop 0
	s_nop 0
	s_nop 0
	s_nop 0
	s_nop 0
	s_nop 0
	s_nop 0
	s_nop 0
	s_nop 0
	s_nop 0
.Lpadj_4:
	s_waitcnt vmcnt(8)
	s_waitcnt lgkmcnt(0)
	s_barrier
	v_mfma_f32_16x16x32_bf16 v[126:129], v[142:145], v[186:189], v[126:129]
	v_mfma_f32_16x16x32_bf16 v[122:125], v[162:165], v[186:189], v[122:125]
	v_mfma_f32_16x16x32_bf16 v[110:113], v[142:145], v[194:197], v[110:113]
	v_mfma_f32_16x16x32_bf16 v[106:109], v[162:165], v[194:197], v[106:109]
	v_mfma_f32_16x16x32_bf16 v[94:97], v[142:145], v[202:205], v[94:97]
	v_mfma_f32_16x16x32_bf16 v[90:93], v[162:165], v[202:205], v[90:93]
	v_mfma_f32_16x16x32_bf16 v[78:81], v[142:145], v[220:223], v[78:81]
	v_mfma_f32_16x16x32_bf16 v[74:77], v[162:165], v[220:223], v[74:77]
	v_mfma_f32_16x16x32_bf16 v[126:129], v[158:161], v[190:193], v[126:129]
	v_mfma_f32_16x16x32_bf16 v[122:125], v[166:169], v[190:193], v[122:125]
	v_mfma_f32_16x16x32_bf16 v[110:113], v[158:161], v[198:201], v[110:113]
	v_mfma_f32_16x16x32_bf16 v[106:109], v[166:169], v[198:201], v[106:109]
	v_mfma_f32_16x16x32_bf16 v[94:97], v[158:161], v[206:209], v[94:97]
	v_mfma_f32_16x16x32_bf16 v[90:93], v[166:169], v[206:209], v[90:93]
	v_mfma_f32_16x16x32_bf16 v[78:81], v[158:161], v[236:239], v[78:81]
	v_mfma_f32_16x16x32_bf16 v[74:77], v[166:169], v[236:239], v[74:77]
	v_mfma_f32_16x16x32_bf16 v[118:121], v[170:173], v[186:189], v[118:121]
	v_mfma_f32_16x16x32_bf16 v[114:117], v[178:181], v[186:189], v[114:117]
	v_mfma_f32_16x16x32_bf16 v[102:105], v[170:173], v[194:197], v[102:105]
	v_mfma_f32_16x16x32_bf16 v[98:101], v[178:181], v[194:197], v[98:101]
	v_mfma_f32_16x16x32_bf16 v[86:89], v[170:173], v[202:205], v[86:89]
	v_mfma_f32_16x16x32_bf16 v[82:85], v[178:181], v[202:205], v[82:85]
	v_mfma_f32_16x16x32_bf16 v[70:73], v[170:173], v[220:223], v[70:73]
	v_mfma_f32_16x16x32_bf16 v[66:69], v[178:181], v[220:223], v[66:69]
	v_mfma_f32_16x16x32_bf16 v[118:121], v[174:177], v[190:193], v[118:121]
	v_mfma_f32_16x16x32_bf16 v[114:117], v[182:185], v[190:193], v[114:117]
	v_mfma_f32_16x16x32_bf16 v[102:105], v[174:177], v[198:201], v[102:105]
	v_mfma_f32_16x16x32_bf16 v[98:101], v[182:185], v[198:201], v[98:101]
	v_mfma_f32_16x16x32_bf16 v[86:89], v[174:177], v[206:209], v[86:89]
	v_mfma_f32_16x16x32_bf16 v[82:85], v[182:185], v[206:209], v[82:85]
	v_mfma_f32_16x16x32_bf16 v[70:73], v[174:177], v[236:239], v[70:73]
	v_mfma_f32_16x16x32_bf16 v[66:69], v[182:185], v[236:239], v[66:69]
	s_barrier
	s_add_i32 s56, s56, s27
	v_lshl_add_u64 v[224:225], s[30:31], 0, v[132:133]
	s_mov_b32 m0, s56
	ds_read_b128 v[186:189], v157 offset:16384
	ds_read_b128 v[190:193], v157 offset:17408
	ds_read_b128 v[194:197], v157 offset:18432
	ds_read_b128 v[198:201], v157 offset:19456
	ds_read_b128 v[202:205], v157 offset:20480
	ds_read_b128 v[206:209], v157 offset:21504
	ds_read_b128 v[220:223], v157 offset:22528
	ds_read_b128 v[236:239], v157 offset:23552
	global_load_lds_dwordx4 v[224:225], off
	s_add_i32 m0, s56, 0x2000
	s_add_u32 s56, s30, 0x40000
	v_lshl_add_u64 v[230:231], s[30:31], 0, v[136:137]
	s_addc_u32 s57, s31, 0
	s_add_i32 s58, s58, s27
	global_load_lds_dwordx4 v[230:231], off
	s_mov_b32 m0, s58
	v_lshl_add_u64 v[242:243], s[34:35], 0, v[134:135]
	global_load_lds_dwordx4 v132, s[56:57]
	s_add_i32 m0, s58, 0x2000
	s_nop 0
	global_load_lds_dwordx4 v136, s[56:57]
	s_mov_b32 m0, s44
	v_lshl_add_u64 v[240:241], s[34:35], 0, v[130:131]
	global_load_lds_dwordx4 v[240:241], off
	s_mov_b32 m0, s45
	s_nop 0
	global_load_lds_dwordx4 v[242:243], off
	s_branch .Lpadj_5
	s_nop 0
	s_nop 0
	s_nop 0
	s_nop 0
	s_nop 0
	s_nop 0
	s_nop 0
	s_nop 0
.Lpadj_5:
	s_waitcnt vmcnt(8)
	s_waitcnt lgkmcnt(0)
	s_barrier
	v_mfma_f32_16x16x32_bf16 v[62:65], v[142:145], v[186:189], v[62:65]
	v_mfma_f32_16x16x32_bf16 v[58:61], v[162:165], v[186:189], v[58:61]
	v_mfma_f32_16x16x32_bf16 v[46:49], v[142:145], v[194:197], v[46:49]
	v_mfma_f32_16x16x32_bf16 v[42:45], v[162:165], v[194:197], v[42:45]
	v_mfma_f32_16x16x32_bf16 v[30:33], v[142:145], v[202:205], v[30:33]
	v_mfma_f32_16x16x32_bf16 v[26:29], v[162:165], v[202:205], v[26:29]
	v_mfma_f32_16x16x32_bf16 v[14:17], v[142:145], v[220:223], v[14:17]
	v_mfma_f32_16x16x32_bf16 v[10:13], v[162:165], v[220:223], v[10:13]
	v_mfma_f32_16x16x32_bf16 v[62:65], v[158:161], v[190:193], v[62:65]
	v_mfma_f32_16x16x32_bf16 v[58:61], v[166:169], v[190:193], v[58:61]
	v_mfma_f32_16x16x32_bf16 v[46:49], v[158:161], v[198:201], v[46:49]
	v_mfma_f32_16x16x32_bf16 v[42:45], v[166:169], v[198:201], v[42:45]
	v_mfma_f32_16x16x32_bf16 v[30:33], v[158:161], v[206:209], v[30:33]
	v_mfma_f32_16x16x32_bf16 v[26:29], v[166:169], v[206:209], v[26:29]
	v_mfma_f32_16x16x32_bf16 v[14:17], v[158:161], v[236:239], v[14:17]
	v_mfma_f32_16x16x32_bf16 v[10:13], v[166:169], v[236:239], v[10:13]
	v_mfma_f32_16x16x32_bf16 v[54:57], v[170:173], v[186:189], v[54:57]
	v_mfma_f32_16x16x32_bf16 v[50:53], v[178:181], v[186:189], v[50:53]
	v_mfma_f32_16x16x32_bf16 v[38:41], v[170:173], v[194:197], v[38:41]
	v_mfma_f32_16x16x32_bf16 v[34:37], v[178:181], v[194:197], v[34:37]
	v_mfma_f32_16x16x32_bf16 v[22:25], v[170:173], v[202:205], v[22:25]
	v_mfma_f32_16x16x32_bf16 v[18:21], v[178:181], v[202:205], v[18:21]
	v_mfma_f32_16x16x32_bf16 v[6:9], v[170:173], v[220:223], v[6:9]
	v_mfma_f32_16x16x32_bf16 v[2:5], v[178:181], v[220:223], v[2:5]
	v_mfma_f32_16x16x32_bf16 v[54:57], v[174:177], v[190:193], v[54:57]
	v_mfma_f32_16x16x32_bf16 v[50:53], v[182:185], v[190:193], v[50:53]
	v_mfma_f32_16x16x32_bf16 v[38:41], v[174:177], v[198:201], v[38:41]
	v_mfma_f32_16x16x32_bf16 v[34:37], v[182:185], v[198:201], v[34:37]
	v_mfma_f32_16x16x32_bf16 v[22:25], v[174:177], v[206:209], v[22:25]
	v_mfma_f32_16x16x32_bf16 v[18:21], v[182:185], v[206:209], v[18:21]
	v_mfma_f32_16x16x32_bf16 v[6:9], v[174:177], v[236:239], v[6:9]
	v_mfma_f32_16x16x32_bf16 v[2:5], v[182:185], v[236:239], v[2:5]
	s_barrier
	s_add_i32 s56, 0, 0x18000
	s_add_i32 s57, 0, 0x1c000
	v_add_u32_e32 v166, s56, v147
	v_add_u32_e32 v182, s57, v147
	ds_read_b128 v[142:145], v166
	ds_read_b128 v[158:161], v166 offset:1024
	ds_read_b128 v[162:165], v166 offset:2048
	ds_read_b128 v[166:169], v166 offset:3072
	ds_read_b128 v[170:173], v182
	ds_read_b128 v[174:177], v182 offset:1024
	ds_read_b128 v[178:181], v182 offset:2048
	ds_read_b128 v[182:185], v182 offset:3072
	s_add_u32 s34, s34, 0x40000
	s_addc_u32 s35, s35, 0
	s_mov_b32 m0, s43
	ds_read_b128 v[186:189], v157 offset:32768
	ds_read_b128 v[190:193], v157 offset:33792
	ds_read_b128 v[194:197], v157 offset:34816
	ds_read_b128 v[198:201], v157 offset:35840
	ds_read_b128 v[202:205], v157 offset:36864
	ds_read_b128 v[206:209], v157 offset:37888
	ds_read_b128 v[220:223], v157 offset:38912
	ds_read_b128 v[236:239], v157 offset:39936
	global_load_lds_dwordx4 v130, s[34:35]
	s_mov_b32 m0, s46
	s_nop 0
	global_load_lds_dwordx4 v134, s[34:35]
	s_branch .Lpadj_6
	s_nop 0
	s_nop 0
	s_nop 0
	s_nop 0
	s_nop 0
	s_nop 0
	s_nop 0
	s_nop 0
	s_nop 0
	s_nop 0
	s_nop 0
.Lpadj_6:
	s_waitcnt vmcnt(8)
	s_waitcnt lgkmcnt(0)
	s_barrier
	v_mfma_f32_16x16x32_bf16 v[126:129], v[142:145], v[186:189], v[126:129]
	v_mfma_f32_16x16x32_bf16 v[122:125], v[162:165], v[186:189], v[122:125]
	v_mfma_f32_16x16x32_bf16 v[110:113], v[142:145], v[194:197], v[110:113]
	v_mfma_f32_16x16x32_bf16 v[106:109], v[162:165], v[194:197], v[106:109]
	v_mfma_f32_16x16x32_bf16 v[94:97], v[142:145], v[202:205], v[94:97]
	v_mfma_f32_16x16x32_bf16 v[90:93], v[162:165], v[202:205], v[90:93]
	v_mfma_f32_16x16x32_bf16 v[78:81], v[142:145], v[220:223], v[78:81]
	v_mfma_f32_16x16x32_bf16 v[74:77], v[162:165], v[220:223], v[74:77]
	v_mfma_f32_16x16x32_bf16 v[126:129], v[158:161], v[190:193], v[126:129]
	v_mfma_f32_16x16x32_bf16 v[122:125], v[166:169], v[190:193], v[122:125]
	v_mfma_f32_16x16x32_bf16 v[110:113], v[158:161], v[198:201], v[110:113]
	v_mfma_f32_16x16x32_bf16 v[106:109], v[166:169], v[198:201], v[106:109]
	v_mfma_f32_16x16x32_bf16 v[94:97], v[158:161], v[206:209], v[94:97]
	v_mfma_f32_16x16x32_bf16 v[90:93], v[166:169], v[206:209], v[90:93]
	v_mfma_f32_16x16x32_bf16 v[78:81], v[158:161], v[236:239], v[78:81]
	v_mfma_f32_16x16x32_bf16 v[74:77], v[166:169], v[236:239], v[74:77]
	v_mfma_f32_16x16x32_bf16 v[118:121], v[170:173], v[186:189], v[118:121]
	v_mfma_f32_16x16x32_bf16 v[114:117], v[178:181], v[186:189], v[114:117]
	v_mfma_f32_16x16x32_bf16 v[102:105], v[170:173], v[194:197], v[102:105]
	v_mfma_f32_16x16x32_bf16 v[98:101], v[178:181], v[194:197], v[98:101]
	v_mfma_f32_16x16x32_bf16 v[86:89], v[170:173], v[202:205], v[86:89]
	v_mfma_f32_16x16x32_bf16 v[82:85], v[178:181], v[202:205], v[82:85]
	v_mfma_f32_16x16x32_bf16 v[70:73], v[170:173], v[220:223], v[70:73]
	v_mfma_f32_16x16x32_bf16 v[66:69], v[178:181], v[220:223], v[66:69]
	v_mfma_f32_16x16x32_bf16 v[118:121], v[174:177], v[190:193], v[118:121]
	v_mfma_f32_16x16x32_bf16 v[114:117], v[182:185], v[190:193], v[114:117]
	v_mfma_f32_16x16x32_bf16 v[102:105], v[174:177], v[198:201], v[102:105]
	v_mfma_f32_16x16x32_bf16 v[98:101], v[182:185], v[198:201], v[98:101]
	v_mfma_f32_16x16x32_bf16 v[86:89], v[174:177], v[206:209], v[86:89]
	v_mfma_f32_16x16x32_bf16 v[82:85], v[182:185], v[206:209], v[82:85]
	v_mfma_f32_16x16x32_bf16 v[70:73], v[174:177], v[236:239], v[70:73]
	v_mfma_f32_16x16x32_bf16 v[66:69], v[182:185], v[236:239], v[66:69]
	s_barrier
	s_add_i32 s34, s56, s27
	v_lshl_add_u64 v[224:225], v[224:225], 0, s[96:97]
	s_mov_b32 m0, s34
	ds_read_b128 v[186:189], v157 offset:49152
	ds_read_b128 v[190:193], v157 offset:50176
	ds_read_b128 v[194:197], v157 offset:51200
	ds_read_b128 v[198:201], v157 offset:52224
	ds_read_b128 v[202:205], v157 offset:53248
	ds_read_b128 v[206:209], v157 offset:54272
	ds_read_b128 v[220:223], v157 offset:55296
	ds_read_b128 v[236:239], v157 offset:56320
	global_load_lds_dwordx4 v[224:225], off
	s_add_i32 m0, s34, 0x2000
	s_add_u32 s30, s30, 0x40080
	v_lshl_add_u64 v[224:225], v[230:231], 0, s[96:97]
	s_addc_u32 s31, s31, 0
	s_add_i32 s34, s57, s27
	global_load_lds_dwordx4 v[224:225], off
	s_mov_b32 m0, s34
	s_nop 0
	global_load_lds_dwordx4 v132, s[30:31]
	s_add_i32 m0, s34, 0x2000
	s_nop 0
	global_load_lds_dwordx4 v136, s[30:31]
	s_mov_b32 m0, s47
	v_lshl_add_u64 v[224:225], v[240:241], 0, s[96:97]
	global_load_lds_dwordx4 v[224:225], off
	s_mov_b32 m0, s48
	v_lshl_add_u64 v[224:225], v[242:243], 0, s[96:97]
	global_load_lds_dwordx4 v[224:225], off
	s_branch .Lpadj_7
	s_nop 0
	s_nop 0
	s_nop 0
	s_nop 0
	s_nop 0
	s_nop 0
	s_nop 0
	s_nop 0

.Lpadj_17:
	s_waitcnt vmcnt(8)
	s_waitcnt lgkmcnt(0)
	s_barrier
	v_mfma_f32_16x16x32_bf16 v[62:65], v[148:151], v[180:183], v[62:65]
	v_mfma_f32_16x16x32_bf16 v[58:61], v[156:159], v[180:183], v[58:61]
	v_mfma_f32_16x16x32_bf16 v[46:49], v[148:151], v[188:191], v[46:49]
	v_mfma_f32_16x16x32_bf16 v[42:45], v[156:159], v[188:191], v[42:45]
	v_mfma_f32_16x16x32_bf16 v[30:33], v[148:151], v[196:199], v[30:33]
	v_mfma_f32_16x16x32_bf16 v[26:29], v[156:159], v[196:199], v[26:29]
	v_mfma_f32_16x16x32_bf16 v[14:17], v[148:151], v[204:207], v[14:17]
	v_mfma_f32_16x16x32_bf16 v[10:13], v[156:159], v[204:207], v[10:13]
	v_mfma_f32_16x16x32_bf16 v[62:65], v[152:155], v[184:187], v[62:65]
	v_mfma_f32_16x16x32_bf16 v[58:61], v[160:163], v[184:187], v[58:61]
	v_mfma_f32_16x16x32_bf16 v[46:49], v[152:155], v[192:195], v[46:49]
	v_mfma_f32_16x16x32_bf16 v[42:45], v[160:163], v[192:195], v[42:45]
	v_mfma_f32_16x16x32_bf16 v[30:33], v[152:155], v[200:203], v[30:33]
	v_mfma_f32_16x16x32_bf16 v[26:29], v[160:163], v[200:203], v[26:29]
	v_mfma_f32_16x16x32_bf16 v[14:17], v[152:155], v[220:223], v[14:17]
	v_mfma_f32_16x16x32_bf16 v[10:13], v[160:163], v[220:223], v[10:13]
	v_mfma_f32_16x16x32_bf16 v[54:57], v[164:167], v[180:183], v[54:57]
	v_mfma_f32_16x16x32_bf16 v[50:53], v[172:175], v[180:183], v[50:53]
	v_mfma_f32_16x16x32_bf16 v[38:41], v[164:167], v[188:191], v[38:41]
	v_mfma_f32_16x16x32_bf16 v[34:37], v[172:175], v[188:191], v[34:37]
	v_mfma_f32_16x16x32_bf16 v[22:25], v[164:167], v[196:199], v[22:25]
	v_mfma_f32_16x16x32_bf16 v[18:21], v[172:175], v[196:199], v[18:21]
	v_mfma_f32_16x16x32_bf16 v[6:9], v[164:167], v[204:207], v[6:9]
	v_mfma_f32_16x16x32_bf16 v[2:5], v[172:175], v[204:207], v[2:5]
	v_mfma_f32_16x16x32_bf16 v[54:57], v[168:171], v[184:187], v[54:57]
	v_mfma_f32_16x16x32_bf16 v[50:53], v[176:179], v[184:187], v[50:53]
	v_mfma_f32_16x16x32_bf16 v[38:41], v[168:171], v[192:195], v[38:41]
	v_mfma_f32_16x16x32_bf16 v[34:37], v[176:179], v[192:195], v[34:37]
	v_mfma_f32_16x16x32_bf16 v[22:25], v[168:171], v[200:203], v[22:25]
	v_mfma_f32_16x16x32_bf16 v[18:21], v[176:179], v[200:203], v[18:21]
	v_mfma_f32_16x16x32_bf16 v[6:9], v[168:171], v[220:223], v[6:9]
	v_mfma_f32_16x16x32_bf16 v[2:5], v[176:179], v[220:223], v[2:5]
	s_barrier
	s_add_i32 s31, 0, 0x18000
	s_add_i32 s64, 0, 0x1c000
	v_add_u32_e32 v160, s31, v146
	v_add_u32_e32 v176, s64, v146
	ds_read_b128 v[148:151], v160
	ds_read_b128 v[152:155], v160 offset:1024
	ds_read_b128 v[156:159], v160 offset:2048
	ds_read_b128 v[160:163], v160 offset:3072
	ds_read_b128 v[164:167], v176
	ds_read_b128 v[168:171], v176 offset:1024
	ds_read_b128 v[172:175], v176 offset:2048
	ds_read_b128 v[176:179], v176 offset:3072
	s_add_u32 s38, s38, s45
	s_addc_u32 s39, s39, 0
	s_mov_b32 m0, s53
	ds_read_b128 v[180:183], v147 offset:32768
	ds_read_b128 v[184:187], v147 offset:33792
	ds_read_b128 v[188:191], v147 offset:34816
	ds_read_b128 v[192:195], v147 offset:35840
	ds_read_b128 v[196:199], v147 offset:36864
	ds_read_b128 v[200:203], v147 offset:37888
	ds_read_b128 v[204:207], v147 offset:38912
	ds_read_b128 v[220:223], v147 offset:39936
	global_load_lds_dwordx4 v130, s[38:39]
	s_mov_b32 m0, s54
	s_nop 0
	global_load_lds_dwordx4 v134, s[38:39]
	s_branch .Lpadj_18
	s_nop 0
	s_nop 0
	s_nop 0
	s_nop 0
	s_nop 0
	s_nop 0
	s_nop 0
	s_nop 0
	s_nop 0
	s_nop 0
	s_nop 0
	s_nop 0

.LBB0_640:
	s_add_u32 s22, s20, 0xfffc0080
	s_addc_u32 s23, s21, -1
	s_add_i32 s46, 0, 0x10000
	s_cmp_eq_u32 s45, 12
	s_cselect_b32 s25, s13, s23
	s_cselect_b32 s24, s19, s22
	v_add_u32_e32 v150, s46, v159
	s_cselect_b32 s23, s11, s44
	s_cselect_b32 s22, s41, s43
	s_add_i32 s48, 0, 0x14000
	ds_read_b128 v[164:167], v150
	ds_read_b128 v[168:171], v150 offset:1024
	ds_read_b128 v[172:175], v150 offset:2048
	ds_read_b128 v[176:179], v150 offset:3072
	v_add_u32_e32 v150, s48, v159
	ds_read_b128 v[180:183], v150
	ds_read_b128 v[184:187], v150 offset:1024
	ds_read_b128 v[188:191], v150 offset:2048
	ds_read_b128 v[192:195], v150 offset:3072
	s_add_i32 m0, s30, 0xc000
	ds_read_b128 v[196:199], v162
	ds_read_b128 v[200:203], v162 offset:1024
	ds_read_b128 v[204:207], v162 offset:2048
	ds_read_b128 v[220:223], v162 offset:3072
	ds_read_b128 v[236:239], v162 offset:4096
	ds_read_b128 v[240:243], v162 offset:5120
	ds_read_b128 v[244:247], v162 offset:6144
	ds_read_b128 v[248:251], v162 offset:7168
	global_load_lds_dwordx4 v140, s[20:21]
	s_add_i32 m0, s30, 0xe000
	s_nop 0
	global_load_lds_dwordx4 v138, s[20:21]
	s_branch .Lpadj_24
	s_nop 0
	s_nop 0
	s_nop 0
	s_nop 0
	s_nop 0
	s_nop 0
	s_nop 0
	s_nop 0
	s_nop 0
	s_nop 0
	s_nop 0
	s_nop 0
.Lpadj_24:
	s_waitcnt vmcnt(8)
	s_waitcnt lgkmcnt(0)
	s_barrier
	v_mfma_f32_16x16x32_bf16 v[126:129], v[164:167], v[196:199], v[126:129]
	v_mfma_f32_16x16x32_bf16 v[122:125], v[172:175], v[196:199], v[122:125]
	v_mfma_f32_16x16x32_bf16 v[118:121], v[164:167], v[204:207], v[118:121]
	v_mfma_f32_16x16x32_bf16 v[114:117], v[172:175], v[204:207], v[114:117]
	v_mfma_f32_16x16x32_bf16 v[110:113], v[164:167], v[236:239], v[110:113]
	v_mfma_f32_16x16x32_bf16 v[106:109], v[172:175], v[236:239], v[106:109]
	v_mfma_f32_16x16x32_bf16 v[102:105], v[164:167], v[244:247], v[102:105]
	v_mfma_f32_16x16x32_bf16 v[98:101], v[172:175], v[244:247], v[98:101]
	v_mfma_f32_16x16x32_bf16 v[126:129], v[168:171], v[200:203], v[126:129]
	v_mfma_f32_16x16x32_bf16 v[122:125], v[176:179], v[200:203], v[122:125]
	v_mfma_f32_16x16x32_bf16 v[118:121], v[168:171], v[220:223], v[118:121]
	v_mfma_f32_16x16x32_bf16 v[114:117], v[176:179], v[220:223], v[114:117]
	v_mfma_f32_16x16x32_bf16 v[110:113], v[168:171], v[240:243], v[110:113]
	v_mfma_f32_16x16x32_bf16 v[106:109], v[176:179], v[240:243], v[106:109]
	v_mfma_f32_16x16x32_bf16 v[102:105], v[168:171], v[248:251], v[102:105]
	v_mfma_f32_16x16x32_bf16 v[98:101], v[176:179], v[248:251], v[98:101]
	v_mfma_f32_16x16x32_bf16 v[94:97], v[180:183], v[196:199], v[94:97]
	v_mfma_f32_16x16x32_bf16 v[90:93], v[188:191], v[196:199], v[90:93]
	v_mfma_f32_16x16x32_bf16 v[86:89], v[180:183], v[204:207], v[86:89]
	v_mfma_f32_16x16x32_bf16 v[82:85], v[188:191], v[204:207], v[82:85]
	v_mfma_f32_16x16x32_bf16 v[78:81], v[180:183], v[236:239], v[78:81]
	v_mfma_f32_16x16x32_bf16 v[74:77], v[188:191], v[236:239], v[74:77]
	v_mfma_f32_16x16x32_bf16 v[70:73], v[180:183], v[244:247], v[70:73]
	v_mfma_f32_16x16x32_bf16 v[66:69], v[188:191], v[244:247], v[66:69]
	v_mfma_f32_16x16x32_bf16 v[94:97], v[184:187], v[200:203], v[94:97]
	v_mfma_f32_16x16x32_bf16 v[90:93], v[192:195], v[200:203], v[90:93]
	v_mfma_f32_16x16x32_bf16 v[86:89], v[184:187], v[220:223], v[86:89]
	v_mfma_f32_16x16x32_bf16 v[82:85], v[192:195], v[220:223], v[82:85]
	v_mfma_f32_16x16x32_bf16 v[78:81], v[184:187], v[240:243], v[78:81]
	v_mfma_f32_16x16x32_bf16 v[74:77], v[192:195], v[240:243], v[74:77]
	v_mfma_f32_16x16x32_bf16 v[70:73], v[184:187], v[248:251], v[70:73]
	v_mfma_f32_16x16x32_bf16 v[66:69], v[192:195], v[248:251], v[66:69]
	s_barrier
	s_add_i32 s46, s46, s28
	v_lshl_add_u64 v[150:151], s[22:23], 0, v[134:135]
	s_mov_b32 m0, s46
	ds_read_b128 v[196:199], v162 offset:16384
	ds_read_b128 v[200:203], v162 offset:17408
	ds_read_b128 v[204:207], v162 offset:18432
	ds_read_b128 v[220:223], v162 offset:19456
	ds_read_b128 v[236:239], v162 offset:20480
	ds_read_b128 v[240:243], v162 offset:21504
	ds_read_b128 v[244:247], v162 offset:22528
	ds_read_b128 v[248:251], v162 offset:23552
	global_load_lds_dwordx4 v[150:151], off
	s_add_i32 m0, s46, 0x2000
	s_add_u32 s46, s22, 0x40000
	v_lshl_add_u64 v[208:209], s[22:23], 0, v[130:131]
	s_addc_u32 s47, s23, 0
	s_add_i32 s48, s48, s28
	global_load_lds_dwordx4 v[208:209], off
	s_mov_b32 m0, s48
	v_lshl_add_u64 v[252:253], s[24:25], 0, v[132:133]
	global_load_lds_dwordx4 v134, s[46:47]
	s_add_i32 m0, s48, 0x2000
	s_nop 0
	global_load_lds_dwordx4 v130, s[46:47]
	s_mov_b32 m0, s30
	v_lshl_add_u64 v[224:225], s[24:25], 0, v[136:137]
	global_load_lds_dwordx4 v[224:225], off
	s_mov_b32 m0, s31
	s_nop 0
	global_load_lds_dwordx4 v[252:253], off
	s_branch .Lpadj_25
	s_nop 0
	s_nop 0
	s_nop 0
	s_nop 0
	s_nop 0
	s_nop 0
	s_nop 0
	s_nop 0
.Lpadj_25:
	s_waitcnt vmcnt(8)
	s_waitcnt lgkmcnt(0)
	s_barrier
	v_mfma_f32_16x16x32_bf16 v[62:65], v[164:167], v[196:199], v[62:65]
	v_mfma_f32_16x16x32_bf16 v[58:61], v[172:175], v[196:199], v[58:61]
	v_mfma_f32_16x16x32_bf16 v[54:57], v[164:167], v[204:207], v[54:57]
	v_mfma_f32_16x16x32_bf16 v[50:53], v[172:175], v[204:207], v[50:53]
	v_mfma_f32_16x16x32_bf16 v[46:49], v[164:167], v[236:239], v[46:49]
	v_mfma_f32_16x16x32_bf16 v[42:45], v[172:175], v[236:239], v[42:45]
	v_mfma_f32_16x16x32_bf16 v[38:41], v[164:167], v[244:247], v[38:41]
	v_mfma_f32_16x16x32_bf16 v[34:37], v[172:175], v[244:247], v[34:37]
	v_mfma_f32_16x16x32_bf16 v[62:65], v[168:171], v[200:203], v[62:65]
	v_mfma_f32_16x16x32_bf16 v[58:61], v[176:179], v[200:203], v[58:61]
	v_mfma_f32_16x16x32_bf16 v[54:57], v[168:171], v[220:223], v[54:57]
	v_mfma_f32_16x16x32_bf16 v[50:53], v[176:179], v[220:223], v[50:53]
	v_mfma_f32_16x16x32_bf16 v[46:49], v[168:171], v[240:243], v[46:49]
	v_mfma_f32_16x16x32_bf16 v[42:45], v[176:179], v[240:243], v[42:45]
	v_mfma_f32_16x16x32_bf16 v[38:41], v[168:171], v[248:251], v[38:41]
	v_mfma_f32_16x16x32_bf16 v[34:37], v[176:179], v[248:251], v[34:37]
	v_mfma_f32_16x16x32_bf16 v[30:33], v[180:183], v[196:199], v[30:33]
	v_mfma_f32_16x16x32_bf16 v[26:29], v[188:191], v[196:199], v[26:29]
	v_mfma_f32_16x16x32_bf16 v[22:25], v[180:183], v[204:207], v[22:25]
	v_mfma_f32_16x16x32_bf16 v[18:21], v[188:191], v[204:207], v[18:21]
	v_mfma_f32_16x16x32_bf16 v[14:17], v[180:183], v[236:239], v[14:17]
	v_mfma_f32_16x16x32_bf16 v[10:13], v[188:191], v[236:239], v[10:13]
	v_mfma_f32_16x16x32_bf16 v[6:9], v[180:183], v[244:247], v[6:9]
	v_mfma_f32_16x16x32_bf16 v[2:5], v[188:191], v[244:247], v[2:5]
	v_mfma_f32_16x16x32_bf16 v[30:33], v[184:187], v[200:203], v[30:33]
	v_mfma_f32_16x16x32_bf16 v[26:29], v[192:195], v[200:203], v[26:29]
	v_mfma_f32_16x16x32_bf16 v[22:25], v[184:187], v[220:223], v[22:25]
	v_mfma_f32_16x16x32_bf16 v[18:21], v[192:195], v[220:223], v[18:21]
	v_mfma_f32_16x16x32_bf16 v[14:17], v[184:187], v[240:243], v[14:17]
	v_mfma_f32_16x16x32_bf16 v[10:13], v[192:195], v[240:243], v[10:13]
	v_mfma_f32_16x16x32_bf16 v[6:9], v[184:187], v[248:251], v[6:9]
	v_mfma_f32_16x16x32_bf16 v[2:5], v[192:195], v[248:251], v[2:5]
	s_barrier
	s_add_i32 s46, 0, 0x18000
	v_add_u32_e32 v163, s46, v159
	s_add_i32 s47, 0, 0x1c000
	ds_read_b128 v[164:167], v163
	ds_read_b128 v[168:171], v163 offset:1024
	ds_read_b128 v[172:175], v163 offset:2048
	ds_read_b128 v[176:179], v163 offset:3072
	v_add_u32_e32 v163, s47, v159
	ds_read_b128 v[180:183], v163
	ds_read_b128 v[184:187], v163 offset:1024
	ds_read_b128 v[188:191], v163 offset:2048
	ds_read_b128 v[192:195], v163 offset:3072
	s_add_u32 s24, s24, 0x40000
	s_addc_u32 s25, s25, 0
	s_mov_b32 m0, s34
	ds_read_b128 v[196:199], v162 offset:32768
	ds_read_b128 v[200:203], v162 offset:33792
	ds_read_b128 v[204:207], v162 offset:34816
	ds_read_b128 v[220:223], v162 offset:35840
	ds_read_b128 v[236:239], v162 offset:36864
	ds_read_b128 v[240:243], v162 offset:37888
	ds_read_b128 v[244:247], v162 offset:38912
	ds_read_b128 v[248:251], v162 offset:39936
	global_load_lds_dwordx4 v136, s[24:25]
	s_mov_b32 m0, s35
	s_nop 0
	global_load_lds_dwordx4 v132, s[24:25]
	s_branch .Lpadj_26
	s_nop 0
	s_nop 0
	s_nop 0
	s_nop 0
	s_nop 0
	s_nop 0
	s_nop 0
	s_nop 0
	s_nop 0
	s_nop 0
	s_nop 0
.Lpadj_26:
	s_waitcnt vmcnt(8)
	s_waitcnt lgkmcnt(0)
	s_barrier
	v_mfma_f32_16x16x32_bf16 v[126:129], v[164:167], v[196:199], v[126:129]
	v_mfma_f32_16x16x32_bf16 v[122:125], v[172:175], v[196:199], v[122:125]
	v_mfma_f32_16x16x32_bf16 v[118:121], v[164:167], v[204:207], v[118:121]
	v_mfma_f32_16x16x32_bf16 v[114:117], v[172:175], v[204:207], v[114:117]
	v_mfma_f32_16x16x32_bf16 v[110:113], v[164:167], v[236:239], v[110:113]
	v_mfma_f32_16x16x32_bf16 v[106:109], v[172:175], v[236:239], v[106:109]
	v_mfma_f32_16x16x32_bf16 v[102:105], v[164:167], v[244:247], v[102:105]
	v_mfma_f32_16x16x32_bf16 v[98:101], v[172:175], v[244:247], v[98:101]
	v_mfma_f32_16x16x32_bf16 v[126:129], v[168:171], v[200:203], v[126:129]
	v_mfma_f32_16x16x32_bf16 v[122:125], v[176:179], v[200:203], v[122:125]
	v_mfma_f32_16x16x32_bf16 v[118:121], v[168:171], v[220:223], v[118:121]
	v_mfma_f32_16x16x32_bf16 v[114:117], v[176:179], v[220:223], v[114:117]
	v_mfma_f32_16x16x32_bf16 v[110:113], v[168:171], v[240:243], v[110:113]
	v_mfma_f32_16x16x32_bf16 v[106:109], v[176:179], v[240:243], v[106:109]
	v_mfma_f32_16x16x32_bf16 v[102:105], v[168:171], v[248:251], v[102:105]
	v_mfma_f32_16x16x32_bf16 v[98:101], v[176:179], v[248:251], v[98:101]
	v_mfma_f32_16x16x32_bf16 v[94:97], v[180:183], v[196:199], v[94:97]
	v_mfma_f32_16x16x32_bf16 v[90:93], v[188:191], v[196:199], v[90:93]
	v_mfma_f32_16x16x32_bf16 v[86:89], v[180:183], v[204:207], v[86:89]
	v_mfma_f32_16x16x32_bf16 v[82:85], v[188:191], v[204:207], v[82:85]
	v_mfma_f32_16x16x32_bf16 v[78:81], v[180:183], v[236:239], v[78:81]
	v_mfma_f32_16x16x32_bf16 v[74:77], v[188:191], v[236:239], v[74:77]
	v_mfma_f32_16x16x32_bf16 v[70:73], v[180:183], v[244:247], v[70:73]
	v_mfma_f32_16x16x32_bf16 v[66:69], v[188:191], v[244:247], v[66:69]
	v_mfma_f32_16x16x32_bf16 v[94:97], v[184:187], v[200:203], v[94:97]
	v_mfma_f32_16x16x32_bf16 v[90:93], v[192:195], v[200:203], v[90:93]
	v_mfma_f32_16x16x32_bf16 v[86:89], v[184:187], v[220:223], v[86:89]
	v_mfma_f32_16x16x32_bf16 v[82:85], v[192:195], v[220:223], v[82:85]
	v_mfma_f32_16x16x32_bf16 v[78:81], v[184:187], v[240:243], v[78:81]
	v_mfma_f32_16x16x32_bf16 v[74:77], v[192:195], v[240:243], v[74:77]
	v_mfma_f32_16x16x32_bf16 v[70:73], v[184:187], v[248:251], v[70:73]
	v_mfma_f32_16x16x32_bf16 v[66:69], v[192:195], v[248:251], v[66:69]
	s_barrier
	s_add_i32 s24, s46, s28
	v_lshl_add_u64 v[150:151], v[150:151], 0, s[96:97]
	s_mov_b32 m0, s24
	ds_read_b128 v[196:199], v162 offset:49152
	ds_read_b128 v[200:203], v162 offset:50176
	ds_read_b128 v[204:207], v162 offset:51200
	ds_read_b128 v[220:223], v162 offset:52224
	ds_read_b128 v[236:239], v162 offset:53248
	ds_read_b128 v[240:243], v162 offset:54272
	ds_read_b128 v[244:247], v162 offset:55296
	ds_read_b128 v[248:251], v162 offset:56320
	global_load_lds_dwordx4 v[150:151], off
	s_add_i32 m0, s24, 0x2000
	s_add_u32 s22, s22, 0x40080
	v_lshl_add_u64 v[150:151], v[208:209], 0, s[96:97]
	s_addc_u32 s23, s23, 0
	s_add_i32 s24, s47, s28
	global_load_lds_dwordx4 v[150:151], off
	s_mov_b32 m0, s24
	s_nop 0
	global_load_lds_dwordx4 v134, s[22:23]
	s_add_i32 m0, s24, 0x2000
	s_nop 0
	global_load_lds_dwordx4 v130, s[22:23]
	s_mov_b32 m0, s36
	v_lshl_add_u64 v[150:151], v[224:225], 0, s[96:97]
	global_load_lds_dwordx4 v[150:151], off
	s_mov_b32 m0, s37
	v_lshl_add_u64 v[150:151], v[252:253], 0, s[96:97]
	global_load_lds_dwordx4 v[150:151], off
	s_branch .Lpadj_27
	s_nop 0
	s_nop 0
	s_nop 0
	s_nop 0
	s_nop 0
	s_nop 0
	s_nop 0
	s_nop 0
